# v36: phase-2 fragment zero-initialisation as 16 64-bit moves instead of 32 32-bit moves
# baseline (speedup 1.0000x reference)
; #define LAS __attribute__((address_space(3)))
; __device__ __forceinline__ void phase_gla_pre(const Params& P, LAS unsigned char* lds, bool dry) {
;     ...
;         __syncthreads();
;         float run = 0.f;
; #pragma unroll
;         for (int tt = 0; tt < 4; ++tt) {
;             bf16x8 ahi = (bf16x8){0, 0, 0, 0, 0, 0, 0, 0}, alo = ahi;
;             if (g < 2) { const f32x4 l0 = *(const LAS f32x4*)(Llr + (16 * tt + fr) * 16 + 8 * g), l1 = *(const LAS f32x4*)(Llr + (16 * tt + fr) * 16 + 8 * g + 4); split8(l0, l1, ahi, alo); }
.Lp2_hoisted:
.Lp2_join:
	s_waitcnt lgkmcnt(0)
	s_barrier
	v_mov_b64_e32 v[100:101], 0
	v_mov_b64_e32 v[102:103], 0
	v_mov_b64_e32 v[104:105], 0
	v_mov_b64_e32 v[106:107], 0
	s_and_saveexec_b64 s[36:37], s[6:7]
	s_cbranch_execz .LBB0_486
	ds_read_b128 v[30:33], v96
	ds_read_b128 v[34:37], v96 offset:16
	s_waitcnt lgkmcnt(1)
	v_cvt_pk_bf16_f32 v104, v30, v31
	v_lshlrev_b32_e32 v132, 16, v104
	v_and_b32_e32 v133, 0xffff0000, v104
	v_pk_add_f32 v[30:31], v[30:31], v[132:133] neg_lo:[0,1] neg_hi:[0,1]
	v_cvt_pk_bf16_f32 v105, v32, v33
	v_lshlrev_b32_e32 v134, 16, v105
	v_and_b32_e32 v135, 0xffff0000, v105
	v_pk_add_f32 v[32:33], v[32:33], v[134:135] neg_lo:[0,1] neg_hi:[0,1]
	s_waitcnt lgkmcnt(0)
	v_cvt_pk_bf16_f32 v106, v34, v35
	v_lshlrev_b32_e32 v136, 16, v106
	v_and_b32_e32 v137, 0xffff0000, v106
	v_pk_add_f32 v[34:35], v[34:35], v[136:137] neg_lo:[0,1] neg_hi:[0,1]
	v_cvt_pk_bf16_f32 v107, v36, v37
	v_lshlrev_b32_e32 v138, 16, v107
	v_and_b32_e32 v139, 0xffff0000, v107
	v_pk_add_f32 v[36:37], v[36:37], v[138:139] neg_lo:[0,1] neg_hi:[0,1]
	s_nop 0
	v_cvt_pk_bf16_f32 v103, v36, v37
	v_cvt_pk_bf16_f32 v102, v34, v35
	v_cvt_pk_bf16_f32 v101, v32, v33
	v_cvt_pk_bf16_f32 v100, v30, v31

; #define LAS __attribute__((address_space(3)))
; __device__ __forceinline__ void phase_gla_pre(const Params& P, LAS unsigned char* lds, bool dry) {
;     ...
;         for (int tt = 0; tt < 4; ++tt) {
;             bf16x8 ahi = (bf16x8){0, 0, 0, 0, 0, 0, 0, 0}, alo = ahi;
;             if (g < 2) { const f32x4 l0 = *(const LAS f32x4*)(Llr + (16 * tt + fr) * 16 + 8 * g), l1 = *(const LAS f32x4*)(Llr + (16 * tt + fr) * 16 + 8 * g + 4); split8(l0, l1, ahi, alo); }
;             f32x4 acc = (f32x4){bg, bg, bg, bg};
;             acc = __builtin_amdgcn_mfma_f32_16x16x32_bf16(alo, bhi, acc, 0, 0, 0); acc = __builtin_amdgcn_mfma_f32_16x16x32_bf16(ahi, blo, acc, 0, 0, 0); acc = __builtin_amdgcn_mfma_f32_16x16x32_bf16(ahi, bhi, acc, 0, 0, 0);
;             float pr[4];
; #pragma unroll
;             for (int r = 0; r < 4; ++r) { const float lg = acc[r]; const float ls = fminf(lg, 0.f) - __logf(1.0f + __expf(-fabsf(lg))); pr[r] = ls * (1.0f / 16.0f) + (r ? pr[r - 1] : 0.f); }
;             const float T = pr[3];
;             const float u1 = __shfl_up(T, 16), s1 = T + (g >= 1 ? u1 : 0.f);
;             const float u2 = __shfl_up(s1, 32), s2 = s1 + (g >= 2 ? u2 : 0.f);
;             const float base = run + (s2 - T); run += __shfl(s2, 48 + fr);
; #pragma unroll
;             for (int r = 0; r < 4; ++r) *(LAS float*)(Lb + (16 * tt + 4 * g + r) * BP + (16 * w + fr) * 4) = base + pr[r];
.Lp2_nowait1:
	s_and_b32 s98, s38, 0xff
	s_cselect_b32 s98, 0, 1
	s_nop 1
	v_mfma_f32_16x16x32_bf16 v[32:35], v[100:103], v[140:143], v[252:255]
	v_mfma_f32_16x16x32_bf16 v[32:35], v[104:107], v[144:147], v[32:35]
	v_mfma_f32_16x16x32_bf16 v[32:35], v[104:107], v[140:143], v[32:35]
	s_nop 7
	v_min_f32_e32 v36, 0, v32
	v_mul_f32_e64 v32, |v32|, s89
	v_exp_f32_e32 v32, v32
	v_mul_f32_e64 v37, |v33|, s89
	v_exp_f32_e32 v37, v37
	v_add_f32_e32 v32, 1.0, v32
	v_add_f32_e32 v37, 1.0, v37
	v_log_f32_e32 v32, v32
	v_log_f32_e32 v37, v37
	v_mul_f32_e32 v39, 0x3d800000, v32
	v_min_f32_e32 v33, 0, v33
	v_fma_f32 v32, v36, s93, -v39
	v_mul_f32_e32 v36, 0x3d800000, v37
	v_mul_f32_e64 v37, |v34|, s89
	v_exp_f32_e32 v37, v37
	v_fma_f32 v33, v33, s93, -v36
	v_add_f32_e32 v36, 1.0, v37
	s_nop 1
	v_log_f32_e32 v36, v36
	v_add_f32_e32 v37, v33, v32
	v_min_f32_e32 v33, 0, v34
	v_mul_f32_e32 v34, 0x3d800000, v36
	s_nop 0
	v_mul_f32_e64 v36, |v35|, s89
	v_exp_f32_e32 v36, v36
	v_fma_f32 v33, v33, s93, -v34
	v_add_u32_e32 v38, 0x8800, v98
	v_add_f32_e32 v34, 1.0, v36
	s_nop 1
	v_log_f32_e32 v34, v34
	v_add_f32_e32 v36, v33, v37
	v_min_f32_e32 v33, 0, v35
	v_mul_f32_e32 v35, 0x3d800000, v34
	s_nop 1
	v_fma_f32 v33, v33, s93, -v35
	v_add_f32_e32 v34, v33, v36
	ds_bpermute_b32 v33, v83, v34
	s_waitcnt lgkmcnt(0)
	v_cndmask_b32_e64 v33, v33, 0, s[8:9]
	v_add_f32_e32 v33, v33, v34
	ds_bpermute_b32 v35, v84, v33
	s_waitcnt lgkmcnt(0)
	v_cndmask_b32_e64 v35, 0, v35, s[10:11]
	v_add_f32_e32 v33, v35, v33
	v_sub_f32_e32 v35, v33, v34
	ds_bpermute_b32 v33, v85, v33
	v_add_f32_e32 v35, 0, v35
	v_add_f32_e32 v32, v32, v35
	v_add_f32_e32 v37, v37, v35
	ds_write2_b32 v38, v32, v37 offset1:132
	v_add_f32_e32 v32, v36, v35
	v_add_f32_e32 v34, v34, v35
	v_add_u32_e32 v35, 0x8c00, v98
	ds_write2_b32 v35, v32, v34 offset0:8 offset1:140
	v_mov_b64_e32 v[108:109], 0
	v_mov_b64_e32 v[110:111], 0
	v_mov_b64_e32 v[112:113], 0
	v_mov_b64_e32 v[114:115], 0
	s_and_saveexec_b64 s[36:37], s[6:7]
	s_cbranch_execz .LBB0_488
	ds_read_b128 v[34:37], v96 offset:1024
	ds_read_b128 v[38:41], v96 offset:1040
	s_waitcnt lgkmcnt(1)
	v_cvt_pk_bf16_f32 v112, v34, v35
	v_lshlrev_b32_e32 v132, 16, v112
	v_and_b32_e32 v133, 0xffff0000, v112
	v_pk_add_f32 v[34:35], v[34:35], v[132:133] neg_lo:[0,1] neg_hi:[0,1]
	v_cvt_pk_bf16_f32 v113, v36, v37
	v_lshlrev_b32_e32 v134, 16, v113
	v_and_b32_e32 v135, 0xffff0000, v113
	v_pk_add_f32 v[36:37], v[36:37], v[134:135] neg_lo:[0,1] neg_hi:[0,1]
	s_waitcnt lgkmcnt(0)
	v_cvt_pk_bf16_f32 v114, v38, v39
	v_lshlrev_b32_e32 v136, 16, v114
	v_and_b32_e32 v137, 0xffff0000, v114
	v_pk_add_f32 v[38:39], v[38:39], v[136:137] neg_lo:[0,1] neg_hi:[0,1]
	v_cvt_pk_bf16_f32 v115, v40, v41
	v_lshlrev_b32_e32 v138, 16, v115
	v_and_b32_e32 v139, 0xffff0000, v115
	v_pk_add_f32 v[40:41], v[40:41], v[138:139] neg_lo:[0,1] neg_hi:[0,1]
	s_nop 0
	v_cvt_pk_bf16_f32 v111, v40, v41
	v_cvt_pk_bf16_f32 v110, v38, v39
	v_cvt_pk_bf16_f32 v109, v36, v37
	v_cvt_pk_bf16_f32 v108, v34, v35
.LBB0_488:
	s_or_b64 exec, exec, s[36:37]
	s_nop 0
	v_mfma_f32_16x16x32_bf16 v[34:37], v[108:111], v[140:143], v[252:255]
	v_mfma_f32_16x16x32_bf16 v[34:37], v[112:115], v[144:147], v[34:37]
	v_mfma_f32_16x16x32_bf16 v[34:37], v[112:115], v[140:143], v[34:37]
	s_nop 7
	v_min_f32_e32 v38, 0, v34
	v_mul_f32_e64 v34, |v34|, s89
	v_exp_f32_e32 v34, v34
	v_mul_f32_e64 v39, |v35|, s89
	v_exp_f32_e32 v39, v39
	v_add_f32_e32 v34, 1.0, v34
	v_add_f32_e32 v39, 1.0, v39
	v_log_f32_e32 v34, v34
	v_log_f32_e32 v39, v39
	v_mul_f32_e32 v41, 0x3d800000, v34
	v_fma_f32 v34, v38, s93, -v41
	v_mul_f32_e32 v38, 0x3d800000, v39
	v_min_f32_e32 v35, 0, v35
	v_mul_f32_e64 v39, |v36|, s89
	v_exp_f32_e32 v39, v39
	v_fma_f32 v35, v35, s93, -v38
	v_add_f32_e32 v38, 1.0, v39
	v_min_f32_e32 v36, 0, v36
	v_log_f32_e32 v38, v38
	v_add_f32_e32 v35, v35, v34
	v_mul_f32_e32 v39, 0x3d800000, v38
	s_nop 1
	v_mov_b32_e32 v38, v39
	v_mul_f32_e64 v39, |v37|, s89
	v_exp_f32_e32 v39, v39
	v_fma_f32 v36, v36, s93, -v38
	v_add_f32_e32 v38, 1.0, v39
	v_min_f32_e32 v37, 0, v37
	v_add_f32_e32 v36, v36, v35
	v_log_f32_e32 v38, v38
	s_waitcnt lgkmcnt(2)
	v_add_f32_e32 v40, 0, v33
	v_mul_f32_e32 v39, 0x3d800000, v38
	s_nop 1
	v_fma_f32 v37, v37, s93, -v39
	v_add_f32_e32 v37, v37, v36
	ds_bpermute_b32 v38, v83, v37
	s_waitcnt lgkmcnt(0)
	v_cndmask_b32_e64 v38, v38, 0, s[8:9]
	v_add_f32_e32 v38, v38, v37
	ds_bpermute_b32 v39, v84, v38
	s_waitcnt lgkmcnt(0)
	v_cndmask_b32_e64 v33, 0, v39, s[10:11]
	v_add_f32_e32 v33, v33, v38
	v_sub_f32_e32 v38, v33, v37
	ds_bpermute_b32 v41, v85, v33
	v_add_f32_e32 v38, v40, v38
	v_add_f32_e32 v33, v34, v38
	v_add_f32_e32 v34, v35, v38
	v_add_u32_e32 v35, 0xa800, v98
	ds_write2_b32 v35, v33, v34 offset0:64 offset1:196
	v_add_f32_e32 v33, v36, v38
	v_add_f32_e32 v34, v37, v38
	v_add_u32_e32 v35, 0xac00, v98
	ds_write2_b32 v35, v33, v34 offset0:72 offset1:204
	v_mov_b64_e32 v[116:117], 0
	v_mov_b64_e32 v[118:119], 0
	v_mov_b64_e32 v[120:121], 0
	v_mov_b64_e32 v[122:123], 0
	s_and_saveexec_b64 s[36:37], s[6:7]
	s_cbranch_execz .LBB0_490
	ds_read_b128 v[32:35], v96 offset:2048
	ds_read_b128 v[36:39], v96 offset:2064
	s_waitcnt lgkmcnt(1)
	v_cvt_pk_bf16_f32 v120, v32, v33
	v_lshlrev_b32_e32 v132, 16, v120
	v_and_b32_e32 v133, 0xffff0000, v120
	v_pk_add_f32 v[32:33], v[32:33], v[132:133] neg_lo:[0,1] neg_hi:[0,1]
	v_cvt_pk_bf16_f32 v121, v34, v35
	v_lshlrev_b32_e32 v134, 16, v121
	v_and_b32_e32 v135, 0xffff0000, v121
	v_pk_add_f32 v[34:35], v[34:35], v[134:135] neg_lo:[0,1] neg_hi:[0,1]
	s_waitcnt lgkmcnt(0)
	v_cvt_pk_bf16_f32 v122, v36, v37
	v_lshlrev_b32_e32 v136, 16, v122
	v_and_b32_e32 v137, 0xffff0000, v122
	v_pk_add_f32 v[36:37], v[36:37], v[136:137] neg_lo:[0,1] neg_hi:[0,1]
	v_cvt_pk_bf16_f32 v123, v38, v39
	v_lshlrev_b32_e32 v138, 16, v123
	v_and_b32_e32 v139, 0xffff0000, v123
	v_pk_add_f32 v[38:39], v[38:39], v[138:139] neg_lo:[0,1] neg_hi:[0,1]
	s_nop 0
	v_cvt_pk_bf16_f32 v119, v38, v39
	v_cvt_pk_bf16_f32 v118, v36, v37
	v_cvt_pk_bf16_f32 v117, v34, v35
	v_cvt_pk_bf16_f32 v116, v32, v33
; #define LAS __attribute__((address_space(3)))
; __device__ __forceinline__ void phase_gla_pre(const Params& P, LAS unsigned char* lds, bool dry) {
;     ...
;         for (int tt = 0; tt < 4; ++tt) {
;             bf16x8 ahi = (bf16x8){0, 0, 0, 0, 0, 0, 0, 0}, alo = ahi;
;             if (g < 2) { const f32x4 l0 = *(const LAS f32x4*)(Llr + (16 * tt + fr) * 16 + 8 * g), l1 = *(const LAS f32x4*)(Llr + (16 * tt + fr) * 16 + 8 * g + 4); split8(l0, l1, ahi, alo); }
;             f32x4 acc = (f32x4){bg, bg, bg, bg};
;             acc = __builtin_amdgcn_mfma_f32_16x16x32_bf16(alo, bhi, acc, 0, 0, 0); acc = __builtin_amdgcn_mfma_f32_16x16x32_bf16(ahi, blo, acc, 0, 0, 0); acc = __builtin_amdgcn_mfma_f32_16x16x32_bf16(ahi, bhi, acc, 0, 0, 0);
;             float pr[4];
; #pragma unroll
;             for (int r = 0; r < 4; ++r) { const float lg = acc[r]; const float ls = fminf(lg, 0.f) - __logf(1.0f + __expf(-fabsf(lg))); pr[r] = ls * (1.0f / 16.0f) + (r ? pr[r - 1] : 0.f); }
;             const float T = pr[3];
;             const float u1 = __shfl_up(T, 16), s1 = T + (g >= 1 ? u1 : 0.f);
;             const float u2 = __shfl_up(s1, 32), s2 = s1 + (g >= 2 ? u2 : 0.f);
;             const float base = run + (s2 - T); run += __shfl(s2, 48 + fr);
; #pragma unroll
;             for (int r = 0; r < 4; ++r) *(LAS float*)(Lb + (16 * tt + 4 * g + r) * BP + (16 * w + fr) * 4) = base + pr[r];
.LBB0_490:
	s_or_b64 exec, exec, s[36:37]
	s_nop 0
	v_mfma_f32_16x16x32_bf16 v[32:35], v[116:119], v[140:143], v[252:255]
	s_waitcnt lgkmcnt(2)
	v_add_f32_e32 v40, v40, v41
	v_mfma_f32_16x16x32_bf16 v[32:35], v[120:123], v[144:147], v[32:35]
	v_mfma_f32_16x16x32_bf16 v[32:35], v[120:123], v[140:143], v[32:35]
	s_nop 7
	v_min_f32_e32 v36, 0, v32
	v_mul_f32_e64 v32, |v32|, s89
	v_exp_f32_e32 v32, v32
	v_mul_f32_e64 v37, |v33|, s89
	v_exp_f32_e32 v37, v37
	v_add_f32_e32 v32, 1.0, v32
	v_add_f32_e32 v37, 1.0, v37
	v_log_f32_e32 v32, v32
	v_log_f32_e32 v37, v37
	v_mul_f32_e32 v39, 0x3d800000, v32
	v_fma_f32 v32, v36, s93, -v39
	v_mul_f32_e32 v36, 0x3d800000, v37
	v_min_f32_e32 v33, 0, v33
	v_mul_f32_e64 v37, |v34|, s89
	v_exp_f32_e32 v37, v37
	v_fma_f32 v33, v33, s93, -v36
	v_add_f32_e32 v36, 1.0, v37
	v_min_f32_e32 v34, 0, v34
	v_log_f32_e32 v36, v36
	v_add_f32_e32 v33, v33, v32
	v_mul_f32_e32 v37, 0x3d800000, v36
	s_nop 1
	v_mov_b32_e32 v36, v37
	v_mul_f32_e64 v37, |v35|, s89
	v_exp_f32_e32 v37, v37
	v_fma_f32 v34, v34, s93, -v36
	v_add_f32_e32 v36, 1.0, v37
	v_min_f32_e32 v35, 0, v35
	v_add_f32_e32 v34, v34, v33
	v_log_f32_e32 v36, v36
	s_nop 0
	v_mul_f32_e32 v37, 0x3d800000, v36
	s_nop 1
	v_fma_f32 v35, v35, s93, -v37
	v_add_f32_e32 v35, v35, v34
	ds_bpermute_b32 v36, v83, v35
	s_waitcnt lgkmcnt(0)
	v_cndmask_b32_e64 v36, v36, 0, s[8:9]
	v_add_f32_e32 v36, v36, v35
	ds_bpermute_b32 v37, v84, v36
	s_waitcnt lgkmcnt(0)
	v_cndmask_b32_e64 v37, 0, v37, s[10:11]
	v_add_f32_e32 v36, v37, v36
	v_sub_f32_e32 v37, v36, v35
	ds_bpermute_b32 v41, v85, v36
	v_add_f32_e32 v37, v40, v37
	v_add_f32_e32 v32, v32, v37
	v_add_f32_e32 v33, v33, v37
	v_add_u32_e32 v36, 0xca00, v98
	ds_write2_b32 v36, v32, v33 offset1:132
	v_add_f32_e32 v32, v34, v37
	v_add_f32_e32 v33, v35, v37
	v_add_u32_e32 v34, 0xce00, v98
	ds_write2_b32 v34, v32, v33 offset0:8 offset1:140
	v_mov_b64_e32 v[124:125], 0
	v_mov_b64_e32 v[126:127], 0
	v_mov_b64_e32 v[128:129], 0
	v_mov_b64_e32 v[130:131], 0
	s_and_saveexec_b64 s[36:37], s[6:7]
	s_cbranch_execz .LBB0_492
	ds_read_b128 v[32:35], v96 offset:3072
	ds_read_b128 v[36:39], v96 offset:3088
	s_waitcnt lgkmcnt(1)
	v_cvt_pk_bf16_f32 v128, v32, v33
	v_lshlrev_b32_e32 v132, 16, v128
	v_and_b32_e32 v133, 0xffff0000, v128
	v_pk_add_f32 v[32:33], v[32:33], v[132:133] neg_lo:[0,1] neg_hi:[0,1]
	v_cvt_pk_bf16_f32 v129, v34, v35
	v_lshlrev_b32_e32 v134, 16, v129
	v_and_b32_e32 v135, 0xffff0000, v129
	v_pk_add_f32 v[34:35], v[34:35], v[134:135] neg_lo:[0,1] neg_hi:[0,1]
	s_waitcnt lgkmcnt(0)
	v_cvt_pk_bf16_f32 v130, v36, v37
	v_lshlrev_b32_e32 v136, 16, v130
	v_and_b32_e32 v137, 0xffff0000, v130
	v_pk_add_f32 v[36:37], v[36:37], v[136:137] neg_lo:[0,1] neg_hi:[0,1]
	v_cvt_pk_bf16_f32 v131, v38, v39
	v_lshlrev_b32_e32 v138, 16, v131
	v_and_b32_e32 v139, 0xffff0000, v131
	v_pk_add_f32 v[38:39], v[38:39], v[138:139] neg_lo:[0,1] neg_hi:[0,1]
	s_nop 0
	v_cvt_pk_bf16_f32 v127, v38, v39
	v_cvt_pk_bf16_f32 v126, v36, v37
	v_cvt_pk_bf16_f32 v125, v34, v35
	v_cvt_pk_bf16_f32 v124, v32, v33
